# hyena lag loops rewritten as software-pipelined three-range loops (no exec masking, prefetch next lag)
# speedup vs baseline: 1.0623x; 1.0314x over previous
; DI float bf2f(bf16_t v) { return __uint_as_float(((unsigned)v) << 16); }
; DI unsigned pack2(float lo, float hi) { unsigned r; asm("v_cvt_pk_bf16_f32 %0, %1, %2" : "=v"(r) : "v"(lo), "v"(hi)); return r; }
; DI void hyena_lat_item(const Params& p, int layer, int it, unsigned char* smem) {
;     ...
;     bf16_t* HY = (bf16_t*)(p.ws + WS_HYOT);
; #pragma unroll
;     for (int n = 0; n < 2; ++n)
; #pragma unroll
;         for (int rg = 0; rg < 4; ++rg) {
;             const int a = 32 * (nbase + n) + li, ii = 8 * rg + 4 * lh; const bf16_t* up = ub + a * 40 + 8 * rg + 4 * (1 - lh);
;             const u32x2 zz = *(const u32x2*)up; const u32x2 pp = *(const u32x2*)(P + (size_t)(512 + ch) * NT + bg * SEQ + 32 * a + ii);
;             float z[4] = { bf2f((bf16_t)(zz.y >> 16)), bf2f((bf16_t)(zz.y & 0xffff)), bf2f((bf16_t)(zz.x >> 16)), bf2f((bf16_t)(zz.x & 0xffff)) };
;             float q[4] = { bf2f((bf16_t)(pp.x & 0xffff)), bf2f((bf16_t)(pp.x >> 16)), bf2f((bf16_t)(pp.y & 0xffff)), bf2f((bf16_t)(pp.y >> 16)) };
;             float o[4];
; #pragma unroll
;             for (int e = 0; e < 4; ++e) o[e] = q[e] * (acc[n][4 * rg + e] * inv1 + z[e] * d1);
;             u32x2 w; w.x = pack2(o[0], o[1]); w.y = pack2(o[2], o[3]); *(u32x2*)(HY + (size_t)ch * NT + bg * SEQ + 32 * a + ii) = w;
;         }
.LBB0_301:
	s_or_b64 exec, exec, s[10:11]
	v_lshlrev_b64 v[0:1], 1, v[56:57]
	v_lshl_add_u64 v[40:41], s[36:37], 0, v[0:1]
	s_mov_b64 s[8:9], 0x1100000
	v_lshl_add_u64 v[76:77], v[40:41], 0, s[8:9]
	v_readlane_b32 s8, v252, 10
	s_add_u32 s0, s8, s0
	v_readlane_b32 s8, v252, 11
	s_addc_u32 s1, s8, s1
	v_lshl_add_u64 v[0:1], s[0:1], 0, v[0:1]
	v_lshlrev_b32_e32 v2, 1, v72
	v_lshl_add_u64 v[40:41], v[76:77], 0, v[2:3]
	v_lshl_add_u64 v[78:79], v[0:1], 0, v[2:3]
	v_lshlrev_b32_e32 v2, 1, v58
	v_lshl_add_u64 v[80:81], v[40:41], 0, v[2:3]
	global_load_dwordx2 v[82:83], v[80:81], off
	global_load_dwordx2 v[84:85], v[80:81], off offset:16
	v_add_u32_e32 v41, v60, v88
	ds_read_b128 v[50:53], v41 offset:2560
	ds_read_b128 v[54:57], v41 offset:2592
	global_load_dwordx2 v[94:95], v[80:81], off offset:32
	v_add_f32_e32 v37, v36, v37
	v_add_u32_e32 v63, v59, v73
	v_mov_b32_e32 v58, v21
	v_mov_b32_e32 v92, v20
	v_add_f32_e32 v20, v37, v38
	v_add_u32_e32 v21, 0x800, v63
	v_alignbit_b32 v42, v71, v70, v96
	v_alignbit_b32 v43, v74, v71, v96
	v_alignbit_b32 v45, v65, v75, v96
	v_alignbit_b32 v46, v67, v66, v96
	v_alignbit_b32 v47, v68, v67, v96
	v_alignbit_b32 v48, v69, v68, v96
	v_alignbit_b32 v49, v64, v69, v96
	v_add_f32_e32 v20, v20, v39
	ds_read2_b64 v[64:67], v21 offset0:64 offset1:66
	ds_read2_b64 v[68:71], v21 offset0:68 offset1:70
	global_load_dwordx2 v[38:39], v[80:81], off offset:48
	v_alignbit_b32 v44, v75, v74, v96
	v_mov_b32_e32 v74, v29
	v_add_f32_e32 v29, 0x358637bd, v20
	v_mov_b32_e32 v72, v31
	v_div_scale_f32 v31, s[0:1], v29, v29, 1.0
	v_mov_b32_e32 v36, v35
	v_rcp_f32_e32 v35, v31
	s_waitcnt lgkmcnt(3)
	s_nop 0
	v_mov_b32_e32 v40, v33
	v_div_scale_f32 v33, vcc, 1.0, v29, 1.0
	v_fma_f32 v37, -v31, v35, 1.0
	v_fmac_f32_e32 v35, v37, v35
	v_mul_f32_e32 v37, v33, v35
	v_fma_f32 v41, -v31, v37, v33
	v_fmac_f32_e32 v37, v41, v35
	v_fma_f32 v31, -v31, v37, v33
	v_div_fmas_f32 v31, v31, v35, v37
	v_mov_b32_e32 v90, v23
	s_waitcnt lgkmcnt(1)
	v_and_b32_e32 v23, 0xffff0000, v64
	v_lshlrev_b32_e32 v91, 16, v64
	v_div_fixup_f32 v60, v31, v29, 1.0
	v_and_b32_e32 v93, 0xffff0000, v65
	v_lshlrev_b32_e32 v59, 16, v65
	s_nop 0
	v_mul_f32_e64 v22, v60, v22
	v_mul_f32_e64 v23, v61, v23
	v_mul_f32_e64 v46, v60, v90
	v_mul_f32_e64 v47, v61, v91
	v_mul_f32_e64 v42, v60, v92
	v_mul_f32_e64 v43, v61, v93
	v_pk_mul_f32 v[44:45], v[60:61], v[58:59]
	v_add_f32_e32 v22, v22, v23
	v_add_f32_e32 v23, v46, v47
	v_add_f32_e32 v29, v42, v43
	v_add_f32_e32 v31, v44, v45
	v_lshl_add_u64 v[20:21], v[78:79], 0, v[2:3]
	v_lshlrev_b32_e32 v42, 1, v62
	v_mov_b32_e32 v43, v3
	v_mov_b32_e32 v88, v25
	v_and_b32_e32 v25, 0xffff0000, v67
	v_lshlrev_b32_e32 v89, 16, v67
	v_mov_b32_e32 v86, v27
	v_and_b32_e32 v27, 0xffff0000, v66
	v_lshlrev_b32_e32 v87, 16, v66
	s_waitcnt lgkmcnt(0)
	v_lshlrev_b32_e32 v75, 16, v69
	v_lshlrev_b32_e32 v73, 16, v68
	v_lshl_add_u64 v[0:1], v[0:1], 0, v[42:43]
	v_lshl_add_u64 v[0:1], v[0:1], 0, v[2:3]
	s_waitcnt vmcnt(3)
	v_and_b32_e32 v41, 0xffff0000, v83
	v_lshlrev_b32_e32 v33, 16, v82
	v_and_b32_e32 v35, 0xffff0000, v82
	v_lshlrev_b32_e32 v37, 16, v83
	v_mul_f32_e32 v23, v23, v41
	v_mul_f32_e32 v29, v29, v33
	v_mul_f32_e32 v31, v31, v35
	v_mul_f32_e32 v33, v22, v37
	v_cvt_pk_bf16_f32 v22, v29, v31
	v_cvt_pk_bf16_f32 v23, v33, v23
	global_store_dwordx2 v[20:21], v[22:23], off
	v_lshl_add_u64 v[22:23], v[76:77], 0, v[42:43]
	v_lshl_add_u64 v[44:45], v[22:23], 0, v[2:3]
	global_load_dwordx2 v[46:47], v[44:45], off
	v_pk_mul_f32 v[22:23], v[60:61], v[24:25]
	s_waitcnt vmcnt(4)
	v_lshlrev_b32_e32 v48, 16, v84
	v_add_f32_e32 v22, v22, v23
	v_mul_f32_e32 v24, v22, v48
	v_pk_mul_f32 v[22:23], v[60:61], v[88:89]
	v_and_b32_e32 v29, 0xffff0000, v84
	v_add_f32_e32 v22, v22, v23
	v_mul_f32_e32 v25, v22, v29
	v_pk_mul_f32 v[22:23], v[60:61], v[26:27]
	v_lshlrev_b32_e32 v31, 16, v85
	v_add_f32_e32 v22, v22, v23
	v_mul_f32_e32 v26, v22, v31
	v_pk_mul_f32 v[22:23], v[60:61], v[86:87]
	v_and_b32_e32 v33, 0xffff0000, v85
	v_add_f32_e32 v22, v22, v23
	v_mul_f32_e32 v23, v22, v33
	v_cvt_pk_bf16_f32 v23, v26, v23
	global_load_dwordx2 v[26:27], v[44:45], off offset:16
	v_cvt_pk_bf16_f32 v22, v24, v25
	global_store_dwordx2 v[20:21], v[22:23], off offset:16
	v_and_b32_e32 v23, 0xffff0000, v69
	v_mov_b32_e32 v22, v28
	v_pk_mul_f32 v[22:23], v[60:61], v[22:23]
	s_waitcnt vmcnt(5)
	v_lshlrev_b32_e32 v24, 16, v94
	v_add_f32_e32 v22, v22, v23
	v_mul_f32_e32 v28, v22, v24
	v_pk_mul_f32 v[22:23], v[60:61], v[74:75]
	v_and_b32_e32 v25, 0xffff0000, v68
	v_and_b32_e32 v29, 0xffff0000, v94
	v_add_f32_e32 v22, v22, v23
	v_mov_b32_e32 v24, v30
	v_mul_f32_e32 v29, v22, v29
	v_pk_mul_f32 v[22:23], v[60:61], v[24:25]
	v_lshlrev_b32_e32 v31, 16, v95
	v_add_f32_e32 v22, v22, v23
	v_mul_f32_e32 v24, v22, v31
	v_pk_mul_f32 v[22:23], v[60:61], v[72:73]
	v_and_b32_e32 v33, 0xffff0000, v95
	v_add_f32_e32 v22, v22, v23
	v_mul_f32_e32 v23, v22, v33
	v_cvt_pk_bf16_f32 v22, v28, v29
	global_load_dwordx2 v[28:29], v[44:45], off offset:32
	v_cvt_pk_bf16_f32 v23, v24, v23
	global_store_dwordx2 v[20:21], v[22:23], off offset:32
	v_and_b32_e32 v23, 0xffff0000, v71
	v_mov_b32_e32 v22, v32
	v_pk_mul_f32 v[22:23], v[60:61], v[22:23]
	s_waitcnt vmcnt(6)
; DI float bf2f(bf16_t v) { return __uint_as_float(((unsigned)v) << 16); }
; DI unsigned pack2(float lo, float hi) { unsigned r; asm("v_cvt_pk_bf16_f32 %0, %1, %2" : "=v"(r) : "v"(lo), "v"(hi)); return r; }
; DI void hyena_lat_item(const Params& p, int layer, int it, unsigned char* smem) {
;     ...
;     bf16_t* HY = (bf16_t*)(p.ws + WS_HYOT);
; #pragma unroll
;     for (int n = 0; n < 2; ++n)
; #pragma unroll
;         for (int rg = 0; rg < 4; ++rg) {
;             const int a = 32 * (nbase + n) + li, ii = 8 * rg + 4 * lh; const bf16_t* up = ub + a * 40 + 8 * rg + 4 * (1 - lh);
;             const u32x2 zz = *(const u32x2*)up; const u32x2 pp = *(const u32x2*)(P + (size_t)(512 + ch) * NT + bg * SEQ + 32 * a + ii);
;             float z[4] = { bf2f((bf16_t)(zz.y >> 16)), bf2f((bf16_t)(zz.y & 0xffff)), bf2f((bf16_t)(zz.x >> 16)), bf2f((bf16_t)(zz.x & 0xffff)) };
;             float q[4] = { bf2f((bf16_t)(pp.x & 0xffff)), bf2f((bf16_t)(pp.x >> 16)), bf2f((bf16_t)(pp.y & 0xffff)), bf2f((bf16_t)(pp.y >> 16)) };
;             float o[4];
; #pragma unroll
;             for (int e = 0; e < 4; ++e) o[e] = q[e] * (acc[n][4 * rg + e] * inv1 + z[e] * d1);
;             u32x2 w; w.x = pack2(o[0], o[1]); w.y = pack2(o[2], o[3]); *(u32x2*)(HY + (size_t)ch * NT + bg * SEQ + 32 * a + ii) = w;
;         }
	v_lshlrev_b32_e32 v24, 16, v38
	v_add_f32_e32 v22, v22, v23
	v_mul_f32_e32 v32, v22, v24
	v_mov_b32_e32 v24, v34
	global_load_dwordx2 v[34:35], v[44:45], off offset:48
	v_lshlrev_b32_e32 v41, 16, v71
	v_pk_mul_f32 v[22:23], v[60:61], v[40:41]
	v_and_b32_e32 v25, 0xffff0000, v70
	v_and_b32_e32 v30, 0xffff0000, v38
	v_add_f32_e32 v22, v22, v23
	v_mul_f32_e32 v30, v22, v30
	v_pk_mul_f32 v[22:23], v[60:61], v[24:25]
	v_lshlrev_b32_e32 v37, 16, v70
	v_lshlrev_b32_e32 v31, 16, v39
	v_add_f32_e32 v22, v22, v23
	v_mul_f32_e32 v31, v22, v31
	v_pk_mul_f32 v[22:23], v[60:61], v[36:37]
	v_and_b32_e32 v33, 0xffff0000, v39
	v_add_f32_e32 v22, v22, v23
	v_add_u32_e32 v36, 0x1000, v63
	v_mul_f32_e32 v33, v22, v33
	ds_read2_b64 v[22:25], v36 offset0:128 offset1:130
	v_cvt_pk_bf16_f32 v30, v32, v30
	v_cvt_pk_bf16_f32 v31, v31, v33
	global_store_dwordx2 v[20:21], v[30:31], off offset:48
	v_mov_b32_e32 v20, v4
	s_waitcnt lgkmcnt(0)
	v_and_b32_e32 v21, 0xffff0000, v23
	v_pk_mul_f32 v[20:21], v[60:61], v[20:21]
	v_and_b32_e32 v31, 0xffff0000, v22
	v_lshlrev_b32_e32 v33, 16, v22
	v_add_f32_e32 v4, v20, v21
	v_lshlrev_b32_e32 v23, 16, v23
	s_waitcnt vmcnt(6)
	v_lshlrev_b32_e32 v22, 16, v46
	v_mul_f32_e32 v20, v4, v22
	v_mov_b32_e32 v22, v5
	v_pk_mul_f32 v[4:5], v[60:61], v[22:23]
	v_and_b32_e32 v30, 0xffff0000, v46
	v_add_f32_e32 v4, v4, v5
	v_mul_f32_e32 v21, v4, v30
	v_mov_b32_e32 v30, v6
	v_pk_mul_f32 v[4:5], v[60:61], v[30:31]
	v_lshlrev_b32_e32 v32, 16, v47
	v_add_f32_e32 v4, v4, v5
	v_mul_f32_e32 v6, v4, v32
	v_mov_b32_e32 v32, v7
	v_pk_mul_f32 v[4:5], v[60:61], v[32:33]
	v_and_b32_e32 v37, 0xffff0000, v47
	v_add_f32_e32 v4, v4, v5
	v_mul_f32_e32 v5, v4, v37
	v_cvt_pk_bf16_f32 v4, v20, v21
	v_cvt_pk_bf16_f32 v5, v6, v5
	global_store_dwordx2 v[0:1], v[4:5], off
	v_and_b32_e32 v5, 0xffff0000, v25
	v_mov_b32_e32 v4, v8
	v_pk_mul_f32 v[4:5], v[60:61], v[4:5]
	v_lshlrev_b32_e32 v7, 16, v25
	s_waitcnt vmcnt(6)
	v_lshlrev_b32_e32 v2, 16, v26
	v_add_f32_e32 v4, v4, v5
	v_mov_b32_e32 v6, v9
	v_mul_f32_e32 v2, v4, v2
	v_pk_mul_f32 v[4:5], v[60:61], v[6:7]
	v_and_b32_e32 v20, 0xffff0000, v26
	v_add_f32_e32 v4, v4, v5
	v_and_b32_e32 v21, 0xffff0000, v24
	v_mul_f32_e32 v8, v4, v20
	v_mov_b32_e32 v20, v10
	v_pk_mul_f32 v[4:5], v[60:61], v[20:21]
	v_lshlrev_b32_e32 v22, 16, v27
	v_add_f32_e32 v4, v4, v5
	v_lshlrev_b32_e32 v23, 16, v24
	v_mul_f32_e32 v9, v4, v22
	v_mov_b32_e32 v22, v11
	v_pk_mul_f32 v[4:5], v[60:61], v[22:23]
	v_and_b32_e32 v24, 0xffff0000, v27
	v_add_f32_e32 v10, v4, v5
	ds_read2_b64 v[4:7], v36 offset0:132 offset1:134
	v_mul_f32_e32 v10, v10, v24
	v_cvt_pk_bf16_f32 v8, v2, v8
	v_cvt_pk_bf16_f32 v9, v9, v10
	global_store_dwordx2 v[0:1], v[8:9], off offset:16
	s_waitcnt lgkmcnt(0)
	v_and_b32_e32 v9, 0xffff0000, v5
	v_mov_b32_e32 v8, v12
	v_pk_mul_f32 v[8:9], v[60:61], v[8:9]
	v_and_b32_e32 v11, 0xffff0000, v4
	v_lshlrev_b32_e32 v21, 16, v4
	s_waitcnt vmcnt(5)
	v_lshlrev_b32_e32 v2, 16, v28
	v_add_f32_e32 v4, v8, v9
	v_lshlrev_b32_e32 v5, 16, v5
	v_mul_f32_e32 v2, v4, v2
	v_mov_b32_e32 v4, v13
	v_pk_mul_f32 v[4:5], v[60:61], v[4:5]
	v_and_b32_e32 v10, 0xffff0000, v28
	v_add_f32_e32 v4, v4, v5
	v_mul_f32_e32 v8, v4, v10
	v_mov_b32_e32 v10, v14
	v_pk_mul_f32 v[4:5], v[60:61], v[10:11]
	v_lshlrev_b32_e32 v20, 16, v29
	v_add_f32_e32 v4, v4, v5
	v_mul_f32_e32 v9, v4, v20
	v_mov_b32_e32 v20, v15
	v_pk_mul_f32 v[4:5], v[60:61], v[20:21]
	v_and_b32_e32 v22, 0xffff0000, v29
	v_add_f32_e32 v4, v4, v5
	v_mul_f32_e32 v5, v4, v22
	v_cvt_pk_bf16_f32 v4, v2, v8
	v_cvt_pk_bf16_f32 v5, v9, v5
	global_store_dwordx2 v[0:1], v[4:5], off offset:32
	v_and_b32_e32 v5, 0xffff0000, v7
	v_mov_b32_e32 v4, v16
	v_pk_mul_f32 v[4:5], v[60:61], v[4:5]
	v_lshlrev_b32_e32 v7, 16, v7
	v_and_b32_e32 v9, 0xffff0000, v6
	v_lshlrev_b32_e32 v11, 16, v6
	s_waitcnt vmcnt(4)
	v_lshlrev_b32_e32 v2, 16, v34
	v_add_f32_e32 v4, v4, v5
	v_mov_b32_e32 v6, v17
	v_mul_f32_e32 v2, v4, v2
	v_pk_mul_f32 v[4:5], v[60:61], v[6:7]
	v_and_b32_e32 v8, 0xffff0000, v34
	v_add_f32_e32 v4, v4, v5
	v_mul_f32_e32 v6, v4, v8
	v_mov_b32_e32 v8, v18
	v_pk_mul_f32 v[4:5], v[60:61], v[8:9]
	v_lshlrev_b32_e32 v10, 16, v35
	v_add_f32_e32 v4, v4, v5
	v_mul_f32_e32 v7, v4, v10
	v_mov_b32_e32 v10, v19
	v_pk_mul_f32 v[4:5], v[60:61], v[10:11]
	v_and_b32_e32 v12, 0xffff0000, v35
	v_add_f32_e32 v4, v4, v5
	v_mul_f32_e32 v5, v4, v12
	v_cvt_pk_bf16_f32 v4, v2, v6
	v_cvt_pk_bf16_f32 v5, v7, v5
	global_store_dwordx2 v[0:1], v[4:5], off offset:48

; #define MFMA(a, b, c) __builtin_amdgcn_mfma_f32_32x32x16_bf16((a), (b), (c), 0, 0, 0)
; DI f32x16 zero16() { f32x16 z; _Pragma("unroll") for (int i = 0; i < 16; ++i) z[i] = 0.f; return z; }
; DI void hy_conv(const bf16_t* ub, const bf16_t* filt, f32x16 (&acc)[2], int nbase, int li, int lh) {
;     const int klo = 32 * nbase - 127, khi = 32 * (nbase + 1) + 31;
;     const int m0 = 4096 + li - 8 * lh - 7;
;     const unsigned sh = (unsigned)(m0 & 1) * 16u;
;     const unsigned* fd0 = (const unsigned*)filt + (m0 >> 1);
;     unsigned raw[10];
;     hy_rawload(fd0 + 16 * klo, raw);
; #pragma unroll 4
;     for (int k = klo; k <= khi; ++k) {
;         u32x4 ua, ub4;
;         ua.x = __builtin_amdgcn_alignbit(raw[1], raw[0], sh); ua.y = __builtin_amdgcn_alignbit(raw[2], raw[1], sh); ua.z = __builtin_amdgcn_alignbit(raw[3], raw[2], sh); ua.w = __builtin_amdgcn_alignbit(raw[4], raw[3], sh);
;         ub4.x = __builtin_amdgcn_alignbit(raw[6], raw[5], sh); ub4.y = __builtin_amdgcn_alignbit(raw[7], raw[6], sh); ub4.z = __builtin_amdgcn_alignbit(raw[8], raw[7], sh); ub4.w = __builtin_amdgcn_alignbit(raw[9], raw[8], sh);
;         const bf16x8 a0 = __builtin_bit_cast(bf16x8, ua), a1 = __builtin_bit_cast(bf16x8, ub4);
;         if (k < khi) hy_rawload(fd0 + 16 * (k + 1), raw);
;         bf16x8 b0[2], b1[2]; bool use[2];
; #pragma unroll
;         for (int n = 0; n < 2; ++n) {
;             const int nn = nbase + n; use[n] = (k >= 32 * nn - 127) && (k <= 32 * nn + 31);
;             const int c = 32 * nn + li - k;
;             const bf16_t* up = ub + c * 40 + 8 * lh;
;             b0[n] = ld8(up); b1[n] = ld8(up + 16);
;         }
; #pragma unroll
;         for (int n = 0; n < 2; ++n) if (use[n]) { acc[n] = MFMA(a0, b0[n], acc[n]); acc[n] = MFMA(a1, b1[n], acc[n]); }
;     }
; DI void hyena_lat_item(const Params& p, int layer, int it, unsigned char* smem) {
;     ...
;     __syncthreads();
;     const float inv0 = 1.f / (red[0] + red[1] + red[2] + red[3] + EPS), inv1 = 1.f / (red[4] + red[5] + red[6] + red[7] + EPS);
;     const float d0 = p.in[I_DSH][layer * 512 + ch], d1 = p.in[I_DSH][layer * 512 + 256 + ch];
;     bf16_t* ub = U + bl * UB;
;     f32x16 acc[2];
;     acc[0] = zero16(); acc[1] = zero16();
;     hy_conv(ub, Fl, acc, nbase, li, lh);
.LBB0_432:
	s_or_b64 exec, exec, s[12:13]
	v_add_u32_e32 v106, 0, v1
	v_cmp_gt_i32_e32 vcc, 8, v70
	s_waitcnt vmcnt(3)
	ds_write_b128 v106, v[4:7] offset:30720
	s_waitcnt vmcnt(2)
	ds_write_b128 v106, v[8:11] offset:34816
	s_waitcnt vmcnt(1)
	ds_write_b128 v106, v[12:15] offset:38912
	s_waitcnt vmcnt(0)
	ds_write_b128 v106, v[16:19] offset:43008
	s_and_saveexec_b64 s[12:13], vcc
	v_lshl_add_u32 v1, v70, 2, 0
	ds_write_b32 v1, v3 offset:47104
	s_or_b64 exec, exec, s[12:13]
	v_readlane_b32 s9, v255, 36
	s_or_b32 s8, s8, s9
	s_ashr_i32 s9, s8, 31
	v_readlane_b32 s40, v253, 0
	s_lshl_b64 s[8:9], s[8:9], 2
	v_readlane_b32 s54, v253, 14
	v_readlane_b32 s55, v253, 15
	s_add_u32 s8, s54, s8
	s_addc_u32 s9, s55, s9
	s_waitcnt lgkmcnt(0)
	s_barrier
	global_load_dword v71, v3, s[8:9]
	global_load_dword v61, v3, s[8:9] offset:1024
	v_lshrrev_b32_e32 v112, 5, v0
	v_ashrrev_i32_e32 v75, 7, v70
	v_and_b32_e32 v97, 31, v70
	v_mul_lo_u32 v0, v75, s38
	v_lshlrev_b32_e32 v74, 3, v112
	v_add_u32_e32 v113, 0, v0
	v_sub_u32_e32 v0, v97, v74
	v_add_u32_e32 v0, 0xff9, v0
	v_and_b32_e32 v98, 64, v70
	v_lshlrev_b32_e32 v96, 4, v0
	v_lshlrev_b32_e32 v0, 1, v0
	v_and_b32_e32 v0, 0x3ffc, v0
	v_or_b32_e32 v101, 0xffffff81, v98
	v_add_u32_e32 v100, 0, v0
	v_lshlrev_b32_e32 v0, 6, v101
	v_add_u32_e32 v0, v100, v0
	v_add_u32_e32 v107, 0x7800, v0
	v_add_u32_e32 v111, 0x7600, v0
	ds_read_b128 v[40:43], v3 offset:47136
	ds_read_b128 v[36:39], v3 offset:47152
	v_add_u32_e32 v108, 0x7808, v0
	ds_read2_b32 v[72:73], v111 offset0:124 offset1:132
	v_add_u32_e32 v109, 0x77e0, v0
	v_add_u32_e32 v110, 0x77e8, v0
	ds_read2_b32 v[80:81], v107 offset1:1
	ds_read2_b32 v[82:83], v108 offset1:1
	ds_read2_b32 v[76:77], v109 offset1:1
	ds_read2_b32 v[78:79], v110 offset1:1
	v_mov_b32_e32 v14, v3
	v_mov_b32_e32 v15, v3
	v_mov_b32_e32 v0, v3
	v_mov_b32_e32 v1, v3
	v_mov_b32_e32 v2, v3
	v_mov_b32_e32 v4, v3
	v_mov_b32_e32 v5, v3
	v_mov_b32_e32 v6, v3
	v_mov_b32_e32 v7, v3
	v_mov_b32_e32 v8, v3
	v_mov_b32_e32 v9, v3
	v_mov_b32_e32 v10, v3
	v_mov_b32_e32 v11, v3
	v_mov_b32_e32 v12, v3
	v_mov_b32_e32 v13, v3
	v_mov_b64_e32 v[34:35], v[14:15]
	v_mov_b64_e32 v[32:33], v[12:13]
	v_mov_b64_e32 v[30:31], v[10:11]
	v_mov_b64_e32 v[28:29], v[8:9]
	v_mov_b64_e32 v[26:27], v[6:7]
	v_mov_b64_e32 v[24:25], v[4:5]
	v_mov_b64_e32 v[22:23], v[2:3]
	v_mov_b64_e32 v[20:21], v[0:1]
	v_mov_b64_e32 v[18:19], v[14:15]
	v_or_b32_e32 v99, 63, v98
	v_lshl_add_u32 v60, v112, 4, v113
	v_or_b32_e32 v102, 31, v98
	v_or_b32_e32 v103, 32, v98
	v_or_b32_e32 v104, 0xffffffa1, v98
	v_or_b32_e32 v105, 62, v98
	s_mov_b64 s[12:13], 0
	v_mov_b64_e32 v[16:17], v[12:13]
	v_mov_b64_e32 v[14:15], v[10:11]
	v_mov_b64_e32 v[12:13], v[8:9]
	v_mov_b64_e32 v[10:11], v[6:7]
	v_mov_b64_e32 v[8:9], v[4:5]
	v_mov_b64_e32 v[6:7], v[2:3]
	v_mov_b64_e32 v[4:5], v[0:1]
	v_mov_b32_e32 v2, v101
	v_readlane_b32 s41, v253, 1
	v_readlane_b32 s42, v253, 2
	v_readlane_b32 s43, v253, 3
	v_readlane_b32 s44, v253, 4
	v_readlane_b32 s45, v253, 5
	v_readlane_b32 s46, v253, 6
	v_readlane_b32 s47, v253, 7
	v_readlane_b32 s48, v253, 8
	v_readlane_b32 s49, v253, 9
	v_readlane_b32 s50, v253, 10
	v_readlane_b32 s51, v253, 11
	v_readlane_b32 s52, v253, 12
	v_readlane_b32 s53, v253, 13
	v_add_u32_e32 v164, 0xffffffe0, v107
	v_add_u32_e32 v165, v98, v97
	v_sub_u32_e32 v165, v165, v101
	v_add_u32_e32 v165, -2, v165
	v_mad_u32_u24 v165, v165, s88, v60
	ds_read2_b32 v[194:195], v164 offset0:0 offset1:1
	ds_read2_b32 v[196:197], v164 offset0:2 offset1:3
	ds_read2_b32 v[198:199], v164 offset0:4 offset1:8
	ds_read2_b32 v[200:201], v164 offset0:9 offset1:10
	ds_read2_b32 v[202:203], v164 offset0:11 offset1:12
	ds_read_b128 v[214:217], v165 offset:2720
	ds_read_b128 v[218:221], v165 offset:2752
	ds_read_b128 v[222:225], v165 offset:5280
	ds_read_b128 v[226:229], v165 offset:5312
	s_mov_b32 s8, 16
.Lhy1_a:
	ds_read2_b32 v[204:205], v164 offset0:16 offset1:17
	ds_read2_b32 v[206:207], v164 offset0:18 offset1:19
	ds_read2_b32 v[208:209], v164 offset0:20 offset1:24
	ds_read2_b32 v[210:211], v164 offset0:25 offset1:26
	ds_read2_b32 v[212:213], v164 offset0:27 offset1:28
	ds_read_b128 v[174:177], v165 offset:2640
	ds_read_b128 v[178:181], v165 offset:2672
	ds_read_b128 v[230:233], v165 offset:5200
	ds_read_b128 v[152:155], v165 offset:5232
	s_waitcnt lgkmcnt(9)
	v_alignbit_b32 v156, v200, v199, v96
	v_alignbit_b32 v157, v201, v200, v96
	v_alignbit_b32 v158, v202, v201, v96
	v_alignbit_b32 v159, v203, v202, v96
	v_alignbit_b32 v160, v195, v194, v96
	v_alignbit_b32 v161, v196, v195, v96
	v_alignbit_b32 v162, v197, v196, v96
	v_alignbit_b32 v163, v198, v197, v96
	s_nop 0
	v_mfma_f32_32x32x16_bf16 v[20:35], v[156:159], v[214:217], v[20:35]
	v_mfma_f32_32x32x16_bf16 v[20:35], v[160:163], v[218:221], v[20:35]
	ds_read2_b32 v[194:195], v164 offset0:32 offset1:33
	ds_read2_b32 v[196:197], v164 offset0:34 offset1:35
	ds_read2_b32 v[198:199], v164 offset0:36 offset1:40
	ds_read2_b32 v[200:201], v164 offset0:41 offset1:42
	ds_read2_b32 v[202:203], v164 offset0:43 offset1:44
	ds_read_b128 v[214:217], v165 offset:2560
	ds_read_b128 v[218:221], v165 offset:2592
	ds_read_b128 v[222:225], v165 offset:5120
	ds_read_b128 v[226:229], v165 offset:5152
	s_waitcnt lgkmcnt(9)
	v_alignbit_b32 v156, v210, v209, v96
	v_alignbit_b32 v157, v211, v210, v96
	v_alignbit_b32 v158, v212, v211, v96
	v_alignbit_b32 v159, v213, v212, v96
	v_alignbit_b32 v160, v205, v204, v96
	v_alignbit_b32 v161, v206, v205, v96
	v_alignbit_b32 v162, v207, v206, v96
	v_alignbit_b32 v163, v208, v207, v96
	s_nop 0
	v_mfma_f32_32x32x16_bf16 v[20:35], v[156:159], v[174:177], v[20:35]
	v_mfma_f32_32x32x16_bf16 v[20:35], v[160:163], v[178:181], v[20:35]
	v_add_u32_e32 v164, 0x80, v164
	v_add_u32_e32 v165, 0xffffff60, v165
	s_sub_u32 s8, s8, 1
	s_cmp_lg_u32 s8, 0
	s_cbranch_scc1 .Lhy1_a
	s_mov_b32 s8, 63
; #define MFMA(a, b, c) __builtin_amdgcn_mfma_f32_32x32x16_bf16((a), (b), (c), 0, 0, 0)
; DI void hy_conv(const bf16_t* ub, const bf16_t* filt, f32x16 (&acc)[2], int nbase, int li, int lh) {
;     const int klo = 32 * nbase - 127, khi = 32 * (nbase + 1) + 31;
;     const int m0 = 4096 + li - 8 * lh - 7;
;     const unsigned sh = (unsigned)(m0 & 1) * 16u;
;     const unsigned* fd0 = (const unsigned*)filt + (m0 >> 1);
;     unsigned raw[10];
;     hy_rawload(fd0 + 16 * klo, raw);
; #pragma unroll 4
;     for (int k = klo; k <= khi; ++k) {
;         u32x4 ua, ub4;
;         ua.x = __builtin_amdgcn_alignbit(raw[1], raw[0], sh); ua.y = __builtin_amdgcn_alignbit(raw[2], raw[1], sh); ua.z = __builtin_amdgcn_alignbit(raw[3], raw[2], sh); ua.w = __builtin_amdgcn_alignbit(raw[4], raw[3], sh);
;         ub4.x = __builtin_amdgcn_alignbit(raw[6], raw[5], sh); ub4.y = __builtin_amdgcn_alignbit(raw[7], raw[6], sh); ub4.z = __builtin_amdgcn_alignbit(raw[8], raw[7], sh); ub4.w = __builtin_amdgcn_alignbit(raw[9], raw[8], sh);
;         const bf16x8 a0 = __builtin_bit_cast(bf16x8, ua), a1 = __builtin_bit_cast(bf16x8, ub4);
;         if (k < khi) hy_rawload(fd0 + 16 * (k + 1), raw);
;         bf16x8 b0[2], b1[2]; bool use[2];
; #pragma unroll
;         for (int n = 0; n < 2; ++n) {
;             const int nn = nbase + n; use[n] = (k >= 32 * nn - 127) && (k <= 32 * nn + 31);
;             const int c = 32 * nn + li - k;
;             const bf16_t* up = ub + c * 40 + 8 * lh;
;             b0[n] = ld8(up); b1[n] = ld8(up + 16);
;         }
; #pragma unroll
;         for (int n = 0; n < 2; ++n) if (use[n]) { acc[n] = MFMA(a0, b0[n], acc[n]); acc[n] = MFMA(a1, b1[n], acc[n]); }
;     }
.Lhy1_b:
	ds_read2_b32 v[204:205], v164 offset0:16 offset1:17
	ds_read2_b32 v[206:207], v164 offset0:18 offset1:19
	ds_read2_b32 v[208:209], v164 offset0:20 offset1:24
	ds_read2_b32 v[210:211], v164 offset0:25 offset1:26
	ds_read2_b32 v[212:213], v164 offset0:27 offset1:28
	ds_read_b128 v[174:177], v165 offset:2640
	ds_read_b128 v[178:181], v165 offset:2672
	ds_read_b128 v[230:233], v165 offset:5200
	ds_read_b128 v[152:155], v165 offset:5232
	s_waitcnt lgkmcnt(9)
	v_alignbit_b32 v156, v200, v199, v96
	v_alignbit_b32 v157, v201, v200, v96
	v_alignbit_b32 v158, v202, v201, v96
	v_alignbit_b32 v159, v203, v202, v96
	v_alignbit_b32 v160, v195, v194, v96
	v_alignbit_b32 v161, v196, v195, v96
	v_alignbit_b32 v162, v197, v196, v96
	v_alignbit_b32 v163, v198, v197, v96
	v_mfma_f32_32x32x16_bf16 v[20:35], v[156:159], v[214:217], v[20:35]
	v_mfma_f32_32x32x16_bf16 v[4:19], v[156:159], v[222:225], v[4:19]
	v_mfma_f32_32x32x16_bf16 v[20:35], v[160:163], v[218:221], v[20:35]
	v_mfma_f32_32x32x16_bf16 v[4:19], v[160:163], v[226:229], v[4:19]
	ds_read2_b32 v[194:195], v164 offset0:32 offset1:33
	ds_read2_b32 v[196:197], v164 offset0:34 offset1:35
	ds_read2_b32 v[198:199], v164 offset0:36 offset1:40
	ds_read2_b32 v[200:201], v164 offset0:41 offset1:42
	ds_read2_b32 v[202:203], v164 offset0:43 offset1:44
	ds_read_b128 v[214:217], v165 offset:2560
	ds_read_b128 v[218:221], v165 offset:2592
	ds_read_b128 v[222:225], v165 offset:5120
	ds_read_b128 v[226:229], v165 offset:5152
	s_waitcnt lgkmcnt(9)
	v_alignbit_b32 v156, v210, v209, v96
	v_alignbit_b32 v157, v211, v210, v96
	v_alignbit_b32 v158, v212, v211, v96
	v_alignbit_b32 v159, v213, v212, v96
	v_alignbit_b32 v160, v205, v204, v96
	v_alignbit_b32 v161, v206, v205, v96
	v_alignbit_b32 v162, v207, v206, v96
	v_alignbit_b32 v163, v208, v207, v96
	v_mfma_f32_32x32x16_bf16 v[20:35], v[156:159], v[174:177], v[20:35]
	v_mfma_f32_32x32x16_bf16 v[4:19], v[156:159], v[230:233], v[4:19]
	v_mfma_f32_32x32x16_bf16 v[20:35], v[160:163], v[178:181], v[20:35]
	v_mfma_f32_32x32x16_bf16 v[4:19], v[160:163], v[152:155], v[4:19]
	v_add_u32_e32 v164, 0x80, v164
	v_add_u32_e32 v165, 0xffffff60, v165
	s_sub_u32 s8, s8, 1
	s_cmp_lg_u32 s8, 0
	s_cbranch_scc1 .Lhy1_b
	ds_read2_b32 v[204:205], v164 offset0:16 offset1:17
	ds_read2_b32 v[206:207], v164 offset0:18 offset1:19
	ds_read2_b32 v[208:209], v164 offset0:20 offset1:24
	ds_read2_b32 v[210:211], v164 offset0:25 offset1:26
	ds_read2_b32 v[212:213], v164 offset0:27 offset1:28
	ds_read_b128 v[174:177], v165 offset:2640
	ds_read_b128 v[178:181], v165 offset:2672
	ds_read_b128 v[230:233], v165 offset:5200
	ds_read_b128 v[152:155], v165 offset:5232
	s_waitcnt lgkmcnt(9)
	v_alignbit_b32 v156, v200, v199, v96
	v_alignbit_b32 v157, v201, v200, v96
	v_alignbit_b32 v158, v202, v201, v96
	v_alignbit_b32 v159, v203, v202, v96
	v_alignbit_b32 v160, v195, v194, v96
	v_alignbit_b32 v161, v196, v195, v96
	v_alignbit_b32 v162, v197, v196, v96
	v_alignbit_b32 v163, v198, v197, v96
	v_mfma_f32_32x32x16_bf16 v[20:35], v[156:159], v[214:217], v[20:35]
	v_mfma_f32_32x32x16_bf16 v[4:19], v[156:159], v[222:225], v[4:19]
	v_mfma_f32_32x32x16_bf16 v[20:35], v[160:163], v[218:221], v[20:35]
	v_mfma_f32_32x32x16_bf16 v[4:19], v[160:163], v[226:229], v[4:19]
	v_add_u32_e32 v164, 64, v164
	v_add_u32_e32 v165, 0xffffffb0, v165
	s_mov_b32 s8, 16
.Lhy1_c:
	ds_read2_b32 v[194:195], v164 offset0:16 offset1:17
	ds_read2_b32 v[196:197], v164 offset0:18 offset1:19
	ds_read2_b32 v[198:199], v164 offset0:20 offset1:24
	ds_read2_b32 v[200:201], v164 offset0:25 offset1:26
	ds_read2_b32 v[202:203], v164 offset0:27 offset1:28
	ds_read_b128 v[214:217], v165 offset:2640
	ds_read_b128 v[218:221], v165 offset:2672
	ds_read_b128 v[222:225], v165 offset:5200
	ds_read_b128 v[226:229], v165 offset:5232
	s_waitcnt lgkmcnt(9)
	v_alignbit_b32 v156, v210, v209, v96
	v_alignbit_b32 v157, v211, v210, v96
	v_alignbit_b32 v158, v212, v211, v96
	v_alignbit_b32 v159, v213, v212, v96
	v_alignbit_b32 v160, v205, v204, v96
	v_alignbit_b32 v161, v206, v205, v96
	v_alignbit_b32 v162, v207, v206, v96
	v_alignbit_b32 v163, v208, v207, v96
	s_nop 0
	v_mfma_f32_32x32x16_bf16 v[4:19], v[156:159], v[230:233], v[4:19]
	v_mfma_f32_32x32x16_bf16 v[4:19], v[160:163], v[152:155], v[4:19]
	ds_read2_b32 v[204:205], v164 offset0:32 offset1:33
	ds_read2_b32 v[206:207], v164 offset0:34 offset1:35
	ds_read2_b32 v[208:209], v164 offset0:36 offset1:40
	ds_read2_b32 v[210:211], v164 offset0:41 offset1:42
	ds_read2_b32 v[212:213], v164 offset0:43 offset1:44
	ds_read_b128 v[174:177], v165 offset:2560
	ds_read_b128 v[178:181], v165 offset:2592
	ds_read_b128 v[230:233], v165 offset:5120
	ds_read_b128 v[152:155], v165 offset:5152
	s_waitcnt lgkmcnt(9)
	v_alignbit_b32 v156, v200, v199, v96
	v_alignbit_b32 v157, v201, v200, v96
	v_alignbit_b32 v158, v202, v201, v96
	v_alignbit_b32 v159, v203, v202, v96
	v_alignbit_b32 v160, v195, v194, v96
	v_alignbit_b32 v161, v196, v195, v96
	v_alignbit_b32 v162, v197, v196, v96
	v_alignbit_b32 v163, v198, v197, v96
	s_nop 0
	v_mfma_f32_32x32x16_bf16 v[4:19], v[156:159], v[222:225], v[4:19]
	v_mfma_f32_32x32x16_bf16 v[4:19], v[160:163], v[226:229], v[4:19]
	v_add_u32_e32 v164, 0x80, v164
	v_add_u32_e32 v165, 0xffffff60, v165
	s_sub_u32 s8, s8, 1
	s_cmp_lg_u32 s8, 0
	s_cbranch_scc1 .Lhy1_c
	s_waitcnt vmcnt(0) lgkmcnt(0)
	s_nop 7
	s_nop 3
	s_branch .LBB0_816
; DI float bf2f(bf16_t v) { return __uint_as_float(((unsigned)v) << 16); }
; DI unsigned pack2(float lo, float hi) { unsigned r; asm("v_cvt_pk_bf16_f32 %0, %1, %2" : "=v"(r) : "v"(lo), "v"(hi)); return r; }
; DI void hyena_lat_item(const Params& p, int layer, int it, unsigned char* smem) {
;     ...
;     { u32x4 sf[4];
; #pragma unroll
;       for (int j = 0; j < 4; ++j) sf[j] = *(const u32x4*)(FL + (size_t)(1 * 256 + ch) * 8192 + (tid + 256 * j) * 8);
; #pragma unroll
;       for (int n = 0; n < 2; ++n)
; #pragma unroll
;         for (int rg = 0; rg < 4; ++rg) {
;             const int a = 32 * (nbase + n) + li, ii = 8 * rg + 4 * lh; bf16_t* up = ub + a * 40 + 8 * rg + 4 * (1 - lh);
;             const u32x2 zz = *(const u32x2*)up; const u32x2 pp = *(const u32x2*)(P + (size_t)(256 + ch) * NT + bg * SEQ + 32 * a + ii);
;             float z[4] = { bf2f((bf16_t)(zz.y >> 16)), bf2f((bf16_t)(zz.y & 0xffff)), bf2f((bf16_t)(zz.x >> 16)), bf2f((bf16_t)(zz.x & 0xffff)) };
;             float q[4] = { bf2f((bf16_t)(pp.x & 0xffff)), bf2f((bf16_t)(pp.x >> 16)), bf2f((bf16_t)(pp.y & 0xffff)), bf2f((bf16_t)(pp.y >> 16)) };
;             float o[4];
; #pragma unroll
;             for (int e = 0; e < 4; ++e) o[e] = q[e] * (acc[n][4 * rg + e] * inv0 + z[e] * d0);
;             u32x2 w; w.x = pack2(o[3], o[2]); w.y = pack2(o[1], o[0]); *(u32x2*)up = w;
;         }
; #pragma unroll
;       for (int j = 0; j < 4; ++j) *(u32x4*)(Fl + (tid + 256 * j) * 8) = sf[j]; }
.LBB0_816:
	s_or_b64 exec, exec, s[12:13]
	v_sub_u32_e32 v0, v97, v99
	v_add_u32_e32 v44, v0, v103
	v_lshl_add_u32 v56, v75, 12, s15
	v_mad_i32_i24 v0, v44, s88, v60
	v_ashrrev_i32_e32 v57, 31, v56
	ds_read_b128 v[90:93], v0 offset:2560
	ds_read_b128 v[114:117], v0 offset:2592
	v_lshl_add_u64 v[0:1], v[56:57], 1, s[36:37]
	s_mov_b64 s[8:9], 0x880000
	v_and_b32_e32 v89, 0x5f, v70
	v_lshl_add_u64 v[84:85], v[0:1], 0, s[8:9]
	v_lshlrev_b32_e32 v2, 6, v89
	v_lshl_add_u64 v[0:1], v[84:85], 0, v[2:3]
	v_mov_b32_e32 v75, v3
	v_lshl_add_u64 v[86:87], v[0:1], 0, v[74:75]
	s_waitcnt lgkmcnt(0)
	s_barrier
	global_load_dwordx2 v[94:95], v[86:87], off
	global_load_dwordx2 v[122:123], v[86:87], off offset:16
	s_add_u32 s8, s10, 0x400000
	v_add_f32_e32 v1, v40, v41
	s_addc_u32 s9, s11, 0
	v_add_f32_e32 v1, v1, v42
	v_mul_i32_i24_e32 v88, 0x50, v44
	v_lshl_add_u64 v[40:41], v[62:63], 1, s[8:9]
	v_lshl_add_u64 v[44:45], v[64:65], 1, s[8:9]
	v_lshl_add_u64 v[48:49], v[66:67], 1, s[8:9]
	v_lshl_add_u64 v[52:53], v[68:69], 1, s[8:9]
	v_add_f32_e32 v1, v1, v43
	global_load_dwordx2 v[132:133], v[86:87], off offset:32
	s_nop 0
	global_load_dwordx4 v[40:43], v[40:41], off
	s_nop 0
	global_load_dwordx4 v[44:47], v[44:45], off
	s_nop 0
	global_load_dwordx4 v[48:51], v[48:49], off
	s_nop 0
	global_load_dwordx4 v[52:55], v[52:53], off
	v_xad_u32 v59, v74, 8, v113
	v_alignbit_b32 v119, v78, v77, v96
	v_alignbit_b32 v120, v79, v78, v96
	v_mov_b32_e32 v78, v31
	v_mad_u32_u24 v31, v89, s88, v59
	v_alignbit_b32 v118, v77, v76, v96
	v_mov_b32_e32 v76, v33
	v_add_u32_e32 v33, 0x800, v31
	ds_read2_b64 v[62:65], v33 offset0:64 offset1:66
	ds_read2_b64 v[66:69], v33 offset0:68 offset1:70
	global_load_dwordx2 v[86:87], v[86:87], off offset:48
	v_add_f32_e32 v1, 0x358637bd, v1
	v_div_scale_f32 v2, s[8:9], v1, v1, 1.0
	v_mov_b32_e32 v126, v27
	v_rcp_f32_e32 v27, v2
	v_mov_b32_e32 v124, v29
	v_mov_b32_e32 v128, v25
	v_div_scale_f32 v25, vcc, 1.0, v1, 1.0
	v_fma_f32 v29, -v2, v27, 1.0
	v_fmac_f32_e32 v27, v29, v27
	v_mul_f32_e32 v29, v25, v27
	v_mov_b32_e32 v0, v35
	v_fma_f32 v35, -v2, v29, v25
	v_fmac_f32_e32 v29, v35, v27
	v_fma_f32 v2, -v2, v29, v25
	v_div_fmas_f32 v2, v2, v27, v29
	v_lshlrev_b32_e32 v58, 2, v112
	v_mov_b32_e32 v112, v21
	s_waitcnt lgkmcnt(1)
	v_and_b32_e32 v21, 0xffff0000, v63
	v_div_fixup_f32 v70, v2, v1, 1.0
	v_lshlrev_b32_e32 v113, 16, v63
	v_pk_mul_f32 v[20:21], v[70:71], v[20:21]
	v_mov_b32_e32 v130, v23
	v_and_b32_e32 v23, 0xffff0000, v62
	v_add_f32_e32 v1, v20, v21
	v_pk_mul_f32 v[20:21], v[70:71], v[112:113]
	v_lshlrev_b32_e32 v131, 16, v62
	v_or_b32_e32 v35, 32, v89
	v_lshlrev_b32_e32 v129, 16, v65
	v_lshlrev_b32_e32 v127, 16, v64
	s_waitcnt lgkmcnt(0)
	v_lshlrev_b32_e32 v125, 16, v67
	v_alignbit_b32 v121, v72, v79, v96
	v_lshlrev_b32_e32 v79, 16, v66
	v_lshlrev_b32_e32 v77, 16, v69
	v_alignbit_b32 v80, v81, v80, v96
	v_alignbit_b32 v81, v82, v81, v96
	v_alignbit_b32 v82, v83, v82, v96
	v_alignbit_b32 v83, v73, v83, v96
	v_mul_u32_u24_e32 v73, 0x50, v89
	v_lshlrev_b32_e32 v72, 5, v89
	s_nop 0
	s_mov_b64 s[10:11], 0
	s_waitcnt vmcnt(7)
	v_lshlrev_b32_e32 v2, 16, v94
	v_mul_f32_e32 v1, v1, v2
	v_add_f32_e32 v2, v20, v21
	v_pk_mul_f32 v[20:21], v[70:71], v[22:23]
	v_and_b32_e32 v25, 0xffff0000, v94
	v_lshlrev_b32_e32 v27, 16, v95
	v_add_f32_e32 v20, v20, v21
	v_mul_f32_e32 v2, v2, v25
	v_mul_f32_e32 v22, v20, v27
	v_pk_mul_f32 v[20:21], v[70:71], v[130:131]
	v_and_b32_e32 v23, 0xffff0000, v65
	v_add_f32_e32 v20, v20, v21
	v_cvt_pk_bf16_f32 v21, v2, v1
	v_lshlrev_b32_e32 v2, 6, v35
	v_lshl_add_u64 v[62:63], v[84:85], 0, v[2:3]
	v_and_b32_e32 v25, 0xffff0000, v64
	v_lshl_add_u64 v[64:65], v[62:63], 0, v[74:75]
	v_and_b32_e32 v29, 0xffff0000, v95
	global_load_dwordx2 v[74:75], v[64:65], off
	v_mul_f32_e32 v20, v20, v29
	v_cvt_pk_bf16_f32 v20, v20, v22
	v_mov_b32_e32 v22, v24
	v_pk_mul_f32 v[22:23], v[70:71], v[22:23]
	s_waitcnt vmcnt(7)
	v_lshlrev_b32_e32 v1, 16, v122
	v_add_f32_e32 v22, v22, v23
	v_mul_f32_e32 v1, v22, v1
	v_pk_mul_f32 v[22:23], v[70:71], v[128:129]
	v_and_b32_e32 v2, 0xffff0000, v122
	v_add_f32_e32 v22, v22, v23
	v_mov_b32_e32 v24, v26
	v_mul_f32_e32 v2, v22, v2
	v_pk_mul_f32 v[22:23], v[70:71], v[24:25]
	v_lshlrev_b32_e32 v27, 16, v123
	v_add_f32_e32 v22, v22, v23
	v_mul_f32_e32 v24, v22, v27
	v_pk_mul_f32 v[22:23], v[70:71], v[126:127]
	v_and_b32_e32 v29, 0xffff0000, v123
	v_add_f32_e32 v22, v22, v23
	v_mul_f32_e32 v22, v22, v29
	v_cvt_pk_bf16_f32 v22, v22, v24
	global_load_dwordx2 v[24:25], v[64:65], off offset:16
	v_cvt_pk_bf16_f32 v23, v2, v1
	ds_write2_b64 v33, v[20:21], v[22:23] offset0:64 offset1:66
	v_and_b32_e32 v21, 0xffff0000, v67
	v_mov_b32_e32 v20, v28
	v_pk_mul_f32 v[20:21], v[70:71], v[20:21]
	s_waitcnt vmcnt(7)
	v_lshlrev_b32_e32 v1, 16, v132
	v_add_f32_e32 v20, v20, v21
	v_mul_f32_e32 v1, v20, v1
	v_pk_mul_f32 v[20:21], v[70:71], v[124:125]
	v_and_b32_e32 v23, 0xffff0000, v66
	v_and_b32_e32 v2, 0xffff0000, v132
	v_add_f32_e32 v20, v20, v21
	v_mov_b32_e32 v22, v30
	v_mul_f32_e32 v2, v20, v2
	v_pk_mul_f32 v[20:21], v[70:71], v[22:23]
	v_lshlrev_b32_e32 v26, 16, v133
	v_add_f32_e32 v20, v20, v21
	global_load_dwordx2 v[28:29], v[64:65], off offset:32
	v_mul_f32_e32 v22, v20, v26
	v_pk_mul_f32 v[20:21], v[70:71], v[78:79]
	v_and_b32_e32 v27, 0xffff0000, v133
	v_add_f32_e32 v20, v20, v21
	v_mul_f32_e32 v20, v20, v27
	v_cvt_pk_bf16_f32 v26, v20, v22
	v_and_b32_e32 v21, 0xffff0000, v69
	v_mov_b32_e32 v20, v32
	v_pk_mul_f32 v[20:21], v[70:71], v[20:21]
	v_cvt_pk_bf16_f32 v27, v2, v1
	s_waitcnt vmcnt(3)
; DI float bf2f(bf16_t v) { return __uint_as_float(((unsigned)v) << 16); }
; DI unsigned pack2(float lo, float hi) { unsigned r; asm("v_cvt_pk_bf16_f32 %0, %1, %2" : "=v"(r) : "v"(lo), "v"(hi)); return r; }
; DI f32x16 zero16() { f32x16 z; _Pragma("unroll") for (int i = 0; i < 16; ++i) z[i] = 0.f; return z; }
; DI void hy_conv(const bf16_t* ub, const bf16_t* filt, f32x16 (&acc)[2], int nbase, int li, int lh) {
;     const int klo = 32 * nbase - 127, khi = 32 * (nbase + 1) + 31;
;     const int m0 = 4096 + li - 8 * lh - 7;
;     const unsigned sh = (unsigned)(m0 & 1) * 16u;
;     const unsigned* fd0 = (const unsigned*)filt + (m0 >> 1);
;     unsigned raw[10];
;     hy_rawload(fd0 + 16 * klo, raw);
; DI void hyena_lat_item(const Params& p, int layer, int it, unsigned char* smem) {
;     ...
;       for (int n = 0; n < 2; ++n)
; #pragma unroll
;         for (int rg = 0; rg < 4; ++rg) {
;             const int a = 32 * (nbase + n) + li, ii = 8 * rg + 4 * lh; bf16_t* up = ub + a * 40 + 8 * rg + 4 * (1 - lh);
;             const u32x2 zz = *(const u32x2*)up; const u32x2 pp = *(const u32x2*)(P + (size_t)(256 + ch) * NT + bg * SEQ + 32 * a + ii);
;             float z[4] = { bf2f((bf16_t)(zz.y >> 16)), bf2f((bf16_t)(zz.y & 0xffff)), bf2f((bf16_t)(zz.x >> 16)), bf2f((bf16_t)(zz.x & 0xffff)) };
;             float q[4] = { bf2f((bf16_t)(pp.x & 0xffff)), bf2f((bf16_t)(pp.x >> 16)), bf2f((bf16_t)(pp.y & 0xffff)), bf2f((bf16_t)(pp.y >> 16)) };
;             float o[4];
; #pragma unroll
;             for (int e = 0; e < 4; ++e) o[e] = q[e] * (acc[n][4 * rg + e] * inv0 + z[e] * d0);
;             u32x2 w; w.x = pack2(o[3], o[2]); w.y = pack2(o[1], o[0]); *(u32x2*)up = w;
;         }
; #pragma unroll
;       for (int j = 0; j < 4; ++j) *(u32x4*)(Fl + (tid + 256 * j) * 8) = sf[j]; }
;     __syncthreads();
;     acc[0] = zero16(); acc[1] = zero16();
;     hy_conv(ub, Fl, acc, nbase, li, lh);
	v_lshlrev_b32_e32 v2, 16, v86
	v_add_f32_e32 v20, v20, v21
	v_mul_f32_e32 v2, v20, v2
	v_pk_mul_f32 v[20:21], v[70:71], v[76:77]
	v_lshlrev_b32_e32 v1, 16, v68
	v_and_b32_e32 v22, 0xffff0000, v86
	v_add_f32_e32 v20, v20, v21
	v_and_b32_e32 v23, 0xffff0000, v68
	v_mul_f32_e32 v32, v20, v22
	v_mov_b32_e32 v22, v34
	v_pk_mul_f32 v[0:1], v[70:71], v[0:1]
	v_and_b32_e32 v62, 0xffff0000, v87
	v_pk_mul_f32 v[20:21], v[70:71], v[22:23]
	v_add_f32_e32 v0, v0, v1
	v_lshlrev_b32_e32 v30, 16, v87
	v_add_f32_e32 v20, v20, v21
	v_mul_f32_e32 v0, v0, v62
	v_mul_f32_e32 v30, v20, v30
	v_cvt_pk_bf16_f32 v0, v0, v30
	v_cvt_pk_bf16_f32 v1, v32, v2
	ds_write2_b64 v33, v[26:27], v[0:1] offset0:68 offset1:70
	global_load_dwordx2 v[32:33], v[64:65], off offset:48
	s_nop 0
	v_add_u32_e32 v34, 0x1000, v31
	ds_read2_b64 v[20:23], v34 offset0:128 offset1:130
	v_lshlrev_b32_e32 v62, 5, v35
	s_waitcnt lgkmcnt(0)
	v_and_b32_e32 v1, 0xffff0000, v21
	v_lshlrev_b32_e32 v21, 16, v21
	s_nop 5
	v_mov_b32_e32 v0, v4
	v_pk_mul_f32 v[0:1], v[70:71], v[0:1]
	v_and_b32_e32 v27, 0xffff0000, v20
	v_lshlrev_b32_e32 v31, 16, v20
	s_waitcnt vmcnt(3)
	v_lshlrev_b32_e32 v2, 16, v74
	v_add_f32_e32 v0, v0, v1
	v_mov_b32_e32 v20, v5
	v_mul_f32_e32 v2, v0, v2
	v_pk_mul_f32 v[0:1], v[70:71], v[20:21]
	v_and_b32_e32 v26, 0xffff0000, v74
	v_add_f32_e32 v0, v0, v1
	v_mul_f32_e32 v4, v0, v26
	v_mov_b32_e32 v26, v6
	v_pk_mul_f32 v[0:1], v[70:71], v[26:27]
	v_lshlrev_b32_e32 v30, 16, v75
	v_add_f32_e32 v0, v0, v1
	v_mul_f32_e32 v5, v0, v30
	v_mov_b32_e32 v30, v7
	v_pk_mul_f32 v[0:1], v[70:71], v[30:31]
	v_and_b32_e32 v35, 0xffff0000, v75
	v_add_f32_e32 v0, v0, v1
	v_mul_f32_e32 v0, v0, v35
	v_cvt_pk_bf16_f32 v0, v0, v5
	v_cvt_pk_bf16_f32 v1, v4, v2
	v_and_b32_e32 v5, 0xffff0000, v23
	v_mov_b32_e32 v4, v8
	v_pk_mul_f32 v[4:5], v[70:71], v[4:5]
	v_lshlrev_b32_e32 v7, 16, v23
	s_waitcnt vmcnt(2)
	v_lshlrev_b32_e32 v2, 16, v24
	v_add_f32_e32 v4, v4, v5
	v_mov_b32_e32 v6, v9
	v_mul_f32_e32 v2, v4, v2
	v_pk_mul_f32 v[4:5], v[70:71], v[6:7]
	v_and_b32_e32 v20, 0xffff0000, v24
	v_add_f32_e32 v4, v4, v5
	v_and_b32_e32 v21, 0xffff0000, v22
	v_mul_f32_e32 v9, v4, v20
	v_mov_b32_e32 v20, v10
	v_pk_mul_f32 v[4:5], v[70:71], v[20:21]
	v_lshlrev_b32_e32 v23, 16, v22
	v_lshlrev_b32_e32 v22, 16, v25
	v_add_f32_e32 v4, v4, v5
	v_mul_f32_e32 v8, v4, v22
	v_mov_b32_e32 v22, v11
	v_pk_mul_f32 v[4:5], v[70:71], v[22:23]
	v_and_b32_e32 v24, 0xffff0000, v25
	v_add_f32_e32 v10, v4, v5
	ds_read2_b64 v[4:7], v34 offset0:132 offset1:134
	v_mul_f32_e32 v10, v10, v24
	v_cvt_pk_bf16_f32 v8, v10, v8
	v_cvt_pk_bf16_f32 v9, v9, v2
	ds_write2_b64 v34, v[0:1], v[8:9] offset0:128 offset1:130
	s_waitcnt lgkmcnt(1)
	v_and_b32_e32 v1, 0xffff0000, v5
	v_mov_b32_e32 v0, v12
	v_pk_mul_f32 v[0:1], v[70:71], v[0:1]
	v_lshlrev_b32_e32 v5, 16, v5
	v_and_b32_e32 v9, 0xffff0000, v4
	v_lshlrev_b32_e32 v11, 16, v4
	s_waitcnt vmcnt(1)
	v_lshlrev_b32_e32 v2, 16, v28
	v_add_f32_e32 v0, v0, v1
	v_mov_b32_e32 v4, v13
	v_mul_f32_e32 v2, v0, v2
	v_pk_mul_f32 v[0:1], v[70:71], v[4:5]
	v_and_b32_e32 v8, 0xffff0000, v28
	v_add_f32_e32 v0, v0, v1
	v_mul_f32_e32 v4, v0, v8
	v_mov_b32_e32 v8, v14
	v_pk_mul_f32 v[0:1], v[70:71], v[8:9]
	v_lshlrev_b32_e32 v10, 16, v29
	v_add_f32_e32 v0, v0, v1
	v_mul_f32_e32 v5, v0, v10
	v_mov_b32_e32 v10, v15
	v_pk_mul_f32 v[0:1], v[70:71], v[10:11]
	v_and_b32_e32 v20, 0xffff0000, v29
	v_add_f32_e32 v0, v0, v1
	v_mul_f32_e32 v0, v0, v20
	v_cvt_pk_bf16_f32 v0, v0, v5
	v_cvt_pk_bf16_f32 v1, v4, v2
	v_and_b32_e32 v5, 0xffff0000, v7
	v_mov_b32_e32 v4, v16
	v_pk_mul_f32 v[4:5], v[70:71], v[4:5]
	v_lshlrev_b32_e32 v7, 16, v7
	v_and_b32_e32 v9, 0xffff0000, v6
	v_lshlrev_b32_e32 v11, 16, v6
	s_waitcnt vmcnt(0)
	v_lshlrev_b32_e32 v2, 16, v32
	v_add_f32_e32 v4, v4, v5
	v_mov_b32_e32 v6, v17
	v_mul_f32_e32 v2, v4, v2
	v_pk_mul_f32 v[4:5], v[70:71], v[6:7]
	v_and_b32_e32 v8, 0xffff0000, v32
	v_add_f32_e32 v4, v4, v5
	v_mul_f32_e32 v6, v4, v8
	v_mov_b32_e32 v8, v18
	v_pk_mul_f32 v[4:5], v[70:71], v[8:9]
	v_lshlrev_b32_e32 v10, 16, v33
	v_add_f32_e32 v4, v4, v5
	v_mul_f32_e32 v7, v4, v10
	v_mov_b32_e32 v10, v19
	v_pk_mul_f32 v[4:5], v[70:71], v[10:11]
	v_and_b32_e32 v12, 0xffff0000, v33
	v_add_f32_e32 v4, v4, v5
	v_mul_f32_e32 v4, v4, v12
	v_cvt_pk_bf16_f32 v4, v4, v7
	v_cvt_pk_bf16_f32 v5, v6, v2
	ds_write2_b64 v34, v[0:1], v[4:5] offset0:132 offset1:134
	ds_write_b128 v106, v[40:43] offset:30720
	ds_write_b128 v106, v[44:47] offset:34816
	ds_write_b128 v106, v[48:51] offset:38912
	ds_write_b128 v106, v[52:55] offset:43008
	s_waitcnt lgkmcnt(0)
	s_barrier
	ds_read2_b32 v[64:65], v111 offset0:124 offset1:132
	ds_read2_b32 v[70:71], v107 offset1:1
	ds_read2_b32 v[74:75], v108 offset1:1
	ds_read2_b32 v[66:67], v109 offset1:1
	ds_read2_b32 v[68:69], v110 offset1:1
	v_mov_b32_e32 v14, v3
	v_mov_b32_e32 v15, v3
	v_mov_b32_e32 v0, v3
	v_mov_b32_e32 v1, v3
	v_mov_b32_e32 v2, v3
	v_mov_b32_e32 v4, v3
	v_mov_b32_e32 v5, v3
	v_mov_b32_e32 v6, v3
	v_mov_b32_e32 v7, v3
	v_mov_b32_e32 v8, v3
	v_mov_b32_e32 v9, v3
	v_mov_b32_e32 v10, v3
	v_mov_b32_e32 v11, v3
	v_mov_b32_e32 v12, v3
	v_mov_b32_e32 v13, v3
	v_mov_b64_e32 v[34:35], v[14:15]
	v_mov_b64_e32 v[32:33], v[12:13]
	v_mov_b64_e32 v[30:31], v[10:11]
	v_mov_b64_e32 v[28:29], v[8:9]
	v_mov_b64_e32 v[26:27], v[6:7]
	v_mov_b64_e32 v[24:25], v[4:5]
	v_mov_b64_e32 v[22:23], v[2:3]
	v_mov_b64_e32 v[20:21], v[0:1]
	v_mov_b64_e32 v[18:19], v[14:15]
	v_mov_b64_e32 v[16:17], v[12:13]
	v_mov_b64_e32 v[14:15], v[10:11]
	v_mov_b64_e32 v[12:13], v[8:9]
	v_mov_b64_e32 v[10:11], v[6:7]
	v_mov_b64_e32 v[8:9], v[4:5]
	v_mov_b64_e32 v[6:7], v[2:3]
	v_mov_b64_e32 v[4:5], v[0:1]
	v_add_u32_e32 v164, 0xffffffe0, v107
	v_add_u32_e32 v165, v98, v97
	v_sub_u32_e32 v165, v165, v101
	v_add_u32_e32 v165, -2, v165
	v_mad_u32_u24 v165, v165, s88, v60
	ds_read2_b32 v[194:195], v164 offset0:0 offset1:1
	ds_read2_b32 v[196:197], v164 offset0:2 offset1:3
	ds_read2_b32 v[198:199], v164 offset0:4 offset1:8
	ds_read2_b32 v[200:201], v164 offset0:9 offset1:10
	ds_read2_b32 v[202:203], v164 offset0:11 offset1:12
	ds_read_b128 v[214:217], v165 offset:2720
	ds_read_b128 v[218:221], v165 offset:2752
	ds_read_b128 v[222:225], v165 offset:5280
	ds_read_b128 v[226:229], v165 offset:5312
	s_mov_b32 s8, 16
